# v14 + P1 start stagger by XCD (8 levels x s_sleep 22)
# speedup vs baseline: 1.0035x; 1.0035x over previous
.LBB0_204:
	s_or_b64 exec, exec, s[0:1]
	v_mov_b32_e32 v8, v214
	s_lshr_b32 s0, s90, 0
	s_and_b32 s0, s0, 7
	s_cmp_eq_u32 s0, 0
	s_cbranch_scc1 .Lstag1_done
.Lstag1_loop:
	s_sleep 22
	s_sub_u32 s0, s0, 1
	s_cmp_lg_u32 s0, 0
	s_cbranch_scc1 .Lstag1_loop
